# MLA steady path rescheduled: rescale check before the QK stream, exp/cvt/row-sum VALU spread evenly across all 20 MFMAs, V fragment reads recycled into consumed K fragment registers
# speedup vs baseline: 1.0487x; 1.0094x over previous
.LBB0_445:
	s_andn2_saveexec_b64 s[86:87], s[86:87]
	s_cbranch_execz .LBB0_456
	v_mfma_f32_32x32x16_bf16 v[80:95], v[112:115], v[152:155], 0
	s_and_b32 s18, s72, 0x4000
	v_or_b32_e32 v173, s18, v194
	v_or_b32_e32 v224, 0x2000, v173
	v_add_u32_e32 v96, v173, v186
	v_add_u32_e32 v97, v224, v186
	v_add_u32_e32 v98, v173, v184
	v_add_u32_e32 v99, v224, v184
	v_add_u32_e32 v100, v173, v183
	v_add_u32_e32 v101, v224, v183
	v_add_u32_e32 v225, v173, v191
	v_add_u32_e32 v226, v224, v191
	v_add_u32_e32 v227, v173, v190
	v_add_u32_e32 v228, v224, v190
	v_add_u32_e32 v173, v173, v187
	v_add_u32_e32 v224, v224, v187
	ds_read_b128 v[174:177], v96
	ds_read_b128 v[204:207], v97
	ds_read_b128 v[208:211], v98
	ds_read_b128 v[212:215], v99
	ds_read_b128 v[216:219], v100
	ds_read_b128 v[220:223], v101
	ds_read_b128 v[230:233], v225
	ds_read_b128 v[234:237], v226
	ds_read_b128 v[238:241], v227
	ds_read_b128 v[242:245], v228
	ds_read_b128 v[246:249], v173
	ds_read_b128 v[250:253], v224
	s_cmp_eq_u32 s73, 0
	s_cselect_b64 s[78:79], -1, 0
	v_add_u32_e32 v173, s69, v198
	v_add_u32_e32 v226, v173, v199
	v_add_u32_e32 v228, v173, v200
	v_add_u32_e32 v254, v173, v201
	v_add_u32_e32 v173, v173, v202
	v_max_f32_e32 v224, v65, v65
	v_max_f32_e32 v225, v64, v64
	v_max_f32_e32 v224, v225, v224
	v_max3_f32 v224, v224, v66, v67
	v_max3_f32 v224, v224, v68, v69
	s_waitcnt lgkmcnt(11)
	v_mfma_f32_32x32x16_bf16 v[96:111], v[174:177], v[116:119], v[80:95]
	v_max3_f32 v224, v224, v70, v71
	v_max3_f32 v224, v224, v72, v73
	v_max3_f32 v224, v224, v74, v75
	v_max3_f32 v224, v224, v76, v77
	v_max3_f32 v224, v224, v78, v79
	v_max3_f32 v224, v224, v48, v49
	s_waitcnt lgkmcnt(10)
	v_mfma_f32_32x32x16_bf16 v[80:95], v[204:207], v[116:119], v[80:95]
	ds_read_b128 v[174:177], v226 offset:32768
	v_max3_f32 v224, v224, v50, v51
	v_max3_f32 v224, v224, v52, v53
	v_max3_f32 v224, v224, v54, v55
	v_max3_f32 v224, v224, v56, v57
	v_max3_f32 v224, v224, v58, v59
	v_max3_f32 v224, v224, v60, v61
	v_max3_f32 v229, v224, v62, v63
	v_cmp_lt_f32_e32 vcc, s29, v229
	s_or_b64 vcc, s[78:79], vcc
	s_waitcnt lgkmcnt(10)
	v_mfma_f32_32x32x16_bf16 v[96:111], v[208:211], v[120:123], v[96:111]
	ds_read_b128 v[204:207], v226 offset:36864
	s_cbranch_vccz .LBB0_450
	v_and_b32_e32 v153, 64, v172
	v_xor_b32_e32 v152, 32, v172
	v_add_u32_e32 v153, 64, v153
	v_cmp_lt_i32_e32 vcc, v152, v153
	v_max_f32_e32 v153, v229, v229
	v_mov_b32_e32 v155, 0
	v_cndmask_b32_e32 v152, v172, v152, vcc
	v_lshlrev_b32_e32 v152, 2, v152
	ds_bpermute_b32 v152, v152, v229
	v_mov_b32_e32 v229, 0
	s_waitcnt lgkmcnt(0)
	v_max_f32_e32 v152, v152, v152
	v_max_f32_e32 v152, v153, v152
	v_cmp_lt_f32_e32 vcc, s30, v152
	s_and_b64 s[18:19], s[78:79], vcc
	v_cmp_lt_f32_e32 vcc, s29, v152
	s_or_b64 s[78:79], vcc, s[18:19]
	s_and_saveexec_b64 s[18:19], s[78:79]
	v_add_f32_e32 v152, v203, v152
	v_cvt_pk_bf16_f32 v152, v152, 0
	v_lshlrev_b32_e32 v152, 16, v152
	v_sub_f32_e32 v229, v152, v203
	v_mov_b32_e32 v203, v152
	s_or_b64 exec, exec, s[18:19]
	v_exp_f32_e64 v152, -v229
	s_mov_b64 vcc, s[8:9]
	v_sub_f32_e32 v64, v64, v229
	v_sub_f32_e32 v65, v65, v229
	v_pk_mul_f32 v[46:47], v[46:47], v[152:153] op_sel_hi:[1,0]
	v_pk_mul_f32 v[44:45], v[44:45], v[152:153] op_sel_hi:[1,0]
	v_pk_mul_f32 v[42:43], v[42:43], v[152:153] op_sel_hi:[1,0]
	v_pk_mul_f32 v[40:41], v[40:41], v[152:153] op_sel_hi:[1,0]
	v_pk_mul_f32 v[38:39], v[38:39], v[152:153] op_sel_hi:[1,0]
	v_pk_mul_f32 v[36:37], v[36:37], v[152:153] op_sel_hi:[1,0]
	v_pk_mul_f32 v[34:35], v[34:35], v[152:153] op_sel_hi:[1,0]
	v_pk_mul_f32 v[32:33], v[32:33], v[152:153] op_sel_hi:[1,0]
	v_pk_mul_f32 v[30:31], v[30:31], v[152:153] op_sel_hi:[1,0]
	v_pk_mul_f32 v[28:29], v[28:29], v[152:153] op_sel_hi:[1,0]
	v_pk_mul_f32 v[26:27], v[26:27], v[152:153] op_sel_hi:[1,0]
	v_pk_mul_f32 v[24:25], v[24:25], v[152:153] op_sel_hi:[1,0]
	v_pk_mul_f32 v[22:23], v[22:23], v[152:153] op_sel_hi:[1,0]
	v_pk_mul_f32 v[20:21], v[20:21], v[152:153] op_sel_hi:[1,0]
	v_pk_mul_f32 v[18:19], v[18:19], v[152:153] op_sel_hi:[1,0]
	v_pk_mul_f32 v[16:17], v[16:17], v[152:153] op_sel_hi:[1,0]
	v_pk_mul_f32 v[14:15], v[14:15], v[152:153] op_sel_hi:[1,0]
	v_pk_mul_f32 v[12:13], v[12:13], v[152:153] op_sel_hi:[1,0]
	v_pk_mul_f32 v[10:11], v[10:11], v[152:153] op_sel_hi:[1,0]
	v_pk_mul_f32 v[8:9], v[8:9], v[152:153] op_sel_hi:[1,0]
	v_pk_mul_f32 v[6:7], v[6:7], v[152:153] op_sel_hi:[1,0]
	v_pk_mul_f32 v[4:5], v[4:5], v[152:153] op_sel_hi:[1,0]
	v_pk_mul_f32 v[2:3], v[2:3], v[152:153] op_sel_hi:[1,0]
	v_pk_mul_f32 v[0:1], v[0:1], v[152:153] op_sel_hi:[1,0]
	v_xor_b32_e32 v152, 0x80000000, v203
	v_sub_f32_e32 v66, v66, v229
	v_sub_f32_e32 v67, v67, v229
	v_sub_f32_e32 v68, v68, v229
	v_sub_f32_e32 v69, v69, v229
	v_sub_f32_e32 v70, v70, v229
	v_sub_f32_e32 v71, v71, v229
	v_sub_f32_e32 v72, v72, v229
	v_sub_f32_e32 v73, v73, v229
	v_sub_f32_e32 v74, v74, v229
	v_sub_f32_e32 v75, v75, v229
	v_sub_f32_e32 v76, v76, v229
	v_sub_f32_e32 v77, v77, v229
	v_sub_f32_e32 v78, v78, v229
	v_sub_f32_e32 v79, v79, v229
	v_sub_f32_e32 v48, v48, v229
	v_sub_f32_e32 v49, v49, v229
	v_sub_f32_e32 v50, v50, v229
	v_sub_f32_e32 v51, v51, v229
	v_sub_f32_e32 v52, v52, v229
	v_sub_f32_e32 v53, v53, v229
	v_sub_f32_e32 v54, v54, v229
	v_sub_f32_e32 v55, v55, v229
	v_sub_f32_e32 v56, v56, v229
	v_sub_f32_e32 v57, v57, v229
	v_sub_f32_e32 v58, v58, v229
	v_sub_f32_e32 v59, v59, v229
	v_sub_f32_e32 v60, v60, v229
	v_sub_f32_e32 v61, v61, v229
	v_sub_f32_e32 v62, v62, v229
	v_sub_f32_e32 v63, v63, v229
	v_cndmask_b32_sdwa v152, v113, v152, vcc dst_sel:DWORD dst_unused:UNUSED_PAD src0_sel:DWORD src1_sel:WORD_1
	v_mov_b32_e32 v154, 0
	v_mov_b32_e32 v153, 0
	s_branch .LBB0_451
.LBB0_450:
	v_mov_b32_e32 v229, 0
.LBB0_451:
	v_exp_f32_e32 v64, v64
	v_exp_f32_e32 v65, v65
	v_exp_f32_e32 v66, v66
	s_waitcnt lgkmcnt(10)
	v_mfma_f32_32x32x16_bf16 v[80:95], v[212:215], v[120:123], v[80:95]
	ds_read_b128 v[208:211], v228 offset:32768
	v_exp_f32_e32 v67, v67
	v_exp_f32_e32 v68, v68
	v_exp_f32_e32 v69, v69
	s_waitcnt lgkmcnt(10)
	v_mfma_f32_32x32x16_bf16 v[96:111], v[216:219], v[124:127], v[96:111]
	ds_read_b128 v[212:215], v228 offset:36864
	v_exp_f32_e32 v70, v70
	v_exp_f32_e32 v71, v71
	v_cvt_pk_bf16_f32 v224, v64, v65
	v_cvt_pk_bf16_f32 v225, v66, v67
	s_waitcnt lgkmcnt(10)
	v_mfma_f32_32x32x16_bf16 v[80:95], v[220:223], v[124:127], v[80:95]
	ds_read_b128 v[216:219], v254 offset:32768
	v_cvt_pk_bf16_f32 v226, v68, v69
	v_cvt_pk_bf16_f32 v227, v70, v71
	v_exp_f32_e32 v72, v72
	v_exp_f32_e32 v73, v73
	s_waitcnt lgkmcnt(4)
	v_mfma_f32_32x32x16_bf16 v[32:47], v[174:177], v[224:227], v[32:47]
	ds_read_b128 v[220:223], v254 offset:36864
	v_exp_f32_e32 v74, v74
	v_exp_f32_e32 v75, v75
	v_exp_f32_e32 v76, v76
	s_waitcnt lgkmcnt(4)
	v_mfma_f32_32x32x16_bf16 v[16:31], v[204:207], v[224:227], v[16:31]
	v_exp_f32_e32 v77, v77
	v_exp_f32_e32 v78, v78
	v_exp_f32_e32 v79, v79
	v_mfma_f32_32x32x16_bf16 v[96:111], v[230:233], v[128:131], v[96:111]
	v_cvt_pk_bf16_f32 v224, v72, v73
	v_cvt_pk_bf16_f32 v225, v74, v75
	v_cvt_pk_bf16_f32 v226, v76, v77
	v_cvt_pk_bf16_f32 v227, v78, v79
	v_exp_f32_e32 v48, v48
	v_mfma_f32_32x32x16_bf16 v[80:95], v[234:237], v[128:131], v[80:95]
	ds_read_b128 v[230:233], v173 offset:32768
	v_exp_f32_e32 v49, v49
	v_exp_f32_e32 v50, v50
	v_exp_f32_e32 v51, v51
	s_waitcnt lgkmcnt(4)
	v_mfma_f32_32x32x16_bf16 v[32:47], v[208:211], v[224:227], v[32:47]
	ds_read_b128 v[234:237], v173 offset:36864
	v_exp_f32_e32 v52, v52
	v_exp_f32_e32 v53, v53
	v_exp_f32_e32 v54, v54
	s_waitcnt lgkmcnt(4)
	v_mfma_f32_32x32x16_bf16 v[16:31], v[212:215], v[224:227], v[16:31]
	v_exp_f32_e32 v55, v55
	v_cvt_pk_bf16_f32 v224, v48, v49
	v_cvt_pk_bf16_f32 v225, v50, v51
	v_cvt_pk_bf16_f32 v226, v52, v53
	v_cvt_pk_bf16_f32 v227, v54, v55
	v_mfma_f32_32x32x16_bf16 v[96:111], v[238:241], v[132:135], v[96:111]
	v_exp_f32_e32 v56, v56
	v_exp_f32_e32 v57, v57
	v_exp_f32_e32 v58, v58
	v_mfma_f32_32x32x16_bf16 v[80:95], v[242:245], v[132:135], v[80:95]
	v_exp_f32_e32 v59, v59
	v_exp_f32_e32 v60, v60
	v_exp_f32_e32 v61, v61
	s_waitcnt lgkmcnt(3)
	v_mfma_f32_32x32x16_bf16 v[32:47], v[216:219], v[224:227], v[32:47]
	v_exp_f32_e32 v62, v62
	v_exp_f32_e32 v63, v63
	v_pk_add_f32 v[64:65], v[48:49], v[64:65]
	s_waitcnt lgkmcnt(2)
	v_mfma_f32_32x32x16_bf16 v[16:31], v[220:223], v[224:227], v[16:31]
	v_cvt_pk_bf16_f32 v224, v56, v57
	v_cvt_pk_bf16_f32 v225, v58, v59
	v_cvt_pk_bf16_f32 v226, v60, v61
	v_cvt_pk_bf16_f32 v227, v62, v63
	v_pk_add_f32 v[66:67], v[50:51], v[66:67]
	v_mfma_f32_32x32x16_bf16 v[96:111], v[246:249], v[136:139], v[96:111]
	v_pk_add_f32 v[68:69], v[52:53], v[68:69]
	v_pk_add_f32 v[70:71], v[54:55], v[70:71]
	v_pk_add_f32 v[72:73], v[56:57], v[72:73]
	v_mfma_f32_32x32x16_bf16 v[80:95], v[250:253], v[136:139], v[80:95]
	v_pk_add_f32 v[74:75], v[58:59], v[74:75]
	v_pk_add_f32 v[76:77], v[60:61], v[76:77]
	v_pk_add_f32 v[78:79], v[62:63], v[78:79]
	s_waitcnt lgkmcnt(1)
	v_mfma_f32_32x32x16_bf16 v[32:47], v[230:233], v[224:227], v[32:47]
	v_pk_add_f32 v[0:1], v[64:65], v[0:1]
	v_pk_add_f32 v[2:3], v[66:67], v[2:3]
	v_pk_add_f32 v[4:5], v[68:69], v[4:5]
	s_waitcnt lgkmcnt(0)
	v_mfma_f32_32x32x16_bf16 v[16:31], v[234:237], v[224:227], v[16:31]
	v_cmp_neq_f32_e32 vcc, 0, v229
	v_pk_add_f32 v[6:7], v[70:71], v[6:7]
	v_pk_add_f32 v[8:9], v[72:73], v[8:9]
	v_pk_add_f32 v[10:11], v[74:75], v[10:11]
	v_pk_add_f32 v[12:13], v[76:77], v[12:13]
	v_pk_add_f32 v[14:15], v[78:79], v[14:15]
	s_cbranch_vccz .LBB0_453
	v_sub_f32_e32 v111, v111, v229
	v_sub_f32_e32 v110, v110, v229
	v_sub_f32_e32 v109, v109, v229
	v_sub_f32_e32 v108, v108, v229
	v_sub_f32_e32 v107, v107, v229
	v_sub_f32_e32 v106, v106, v229
	v_sub_f32_e32 v105, v105, v229
	v_sub_f32_e32 v104, v104, v229
	v_sub_f32_e32 v103, v103, v229
	v_sub_f32_e32 v102, v102, v229
	v_sub_f32_e32 v101, v101, v229
	v_sub_f32_e32 v100, v100, v229
	v_sub_f32_e32 v99, v99, v229
	v_sub_f32_e32 v98, v98, v229
	v_sub_f32_e32 v97, v97, v229
	v_sub_f32_e32 v96, v96, v229
	v_sub_f32_e32 v95, v95, v229
	v_sub_f32_e32 v94, v94, v229
	v_sub_f32_e32 v93, v93, v229
	v_sub_f32_e32 v92, v92, v229
	v_sub_f32_e32 v91, v91, v229
	v_sub_f32_e32 v90, v90, v229
	v_sub_f32_e32 v89, v89, v229
	v_sub_f32_e32 v88, v88, v229
	v_sub_f32_e32 v87, v87, v229
	v_sub_f32_e32 v86, v86, v229
	v_sub_f32_e32 v85, v85, v229
	v_sub_f32_e32 v84, v84, v229
	v_sub_f32_e32 v83, v83, v229
	v_sub_f32_e32 v82, v82, v229
	v_sub_f32_e32 v81, v81, v229
	v_sub_f32_e32 v80, v80, v229

.LBB0_455:
	s_or_b64 exec, exec, s[78:79]
.LBB0_456:
	s_or_b64 exec, exec, s[86:87]
	s_add_i32 s69, s73, 2
	s_cmp_lt_u32 s69, s70
	s_cselect_b64 s[18:19], -1, 0
	s_cmp_ge_u32 s69, s70
	s_cbranch_scc0 .LBB0_463
	s_cmp_ge_u32 s74, s70
	s_cbranch_scc0 .LBB0_466

.Lmo_445:
	s_andn2_saveexec_b64 s[86:87], s[86:87]
	s_cbranch_execz .Lmo_456
	v_mfma_f32_32x32x16_bf16 v[48:63], v[112:115], v[152:155], 0
	s_and_b32 s18, s72, 0x4000
	v_or_b32_e32 v173, s18, v194
	v_or_b32_e32 v224, 0x2000, v173
	v_add_u32_e32 v64, v173, v186
	v_add_u32_e32 v65, v224, v186
	v_add_u32_e32 v66, v173, v184
	v_add_u32_e32 v67, v224, v184
	v_add_u32_e32 v68, v173, v183
	v_add_u32_e32 v69, v224, v183
	v_add_u32_e32 v225, v173, v191
	v_add_u32_e32 v226, v224, v191
	v_add_u32_e32 v227, v173, v190
	v_add_u32_e32 v228, v224, v190
	v_add_u32_e32 v173, v173, v187
	v_add_u32_e32 v224, v224, v187
	ds_read_b128 v[174:177], v64
	ds_read_b128 v[204:207], v65
	ds_read_b128 v[208:211], v66
	ds_read_b128 v[212:215], v67
	ds_read_b128 v[216:219], v68
	ds_read_b128 v[220:223], v69
	ds_read_b128 v[230:233], v225
	ds_read_b128 v[234:237], v226
	ds_read_b128 v[238:241], v227
	ds_read_b128 v[242:245], v228
	ds_read_b128 v[246:249], v173
	ds_read_b128 v[250:253], v224
	s_cmp_eq_u32 s73, 0
	s_cselect_b64 s[78:79], -1, 0
	v_add_u32_e32 v173, s69, v198
	v_add_u32_e32 v226, v173, v199
	v_add_u32_e32 v228, v173, v200
	v_add_u32_e32 v254, v173, v201
	v_add_u32_e32 v173, v173, v202
	v_max_f32_e32 v224, v97, v97
	v_max_f32_e32 v225, v96, v96
	v_max_f32_e32 v224, v225, v224
	v_max3_f32 v224, v224, v98, v99
	v_max3_f32 v224, v224, v100, v101
	s_waitcnt lgkmcnt(11)
	v_mfma_f32_32x32x16_bf16 v[64:79], v[174:177], v[116:119], v[48:63]
	v_max3_f32 v224, v224, v102, v103
	v_max3_f32 v224, v224, v104, v105
	v_max3_f32 v224, v224, v106, v107
	v_max3_f32 v224, v224, v108, v109
	v_max3_f32 v224, v224, v110, v111
	v_max3_f32 v224, v224, v80, v81
	s_waitcnt lgkmcnt(10)
	v_mfma_f32_32x32x16_bf16 v[48:63], v[204:207], v[116:119], v[48:63]
	ds_read_b128 v[174:177], v226 offset:32768
	v_max3_f32 v224, v224, v82, v83
	v_max3_f32 v224, v224, v84, v85
	v_max3_f32 v224, v224, v86, v87
	v_max3_f32 v224, v224, v88, v89
	v_max3_f32 v224, v224, v90, v91
	v_max3_f32 v224, v224, v92, v93
	v_max3_f32 v229, v224, v94, v95
	v_cmp_lt_f32_e32 vcc, s29, v229
	s_or_b64 vcc, s[78:79], vcc
	s_waitcnt lgkmcnt(10)
	v_mfma_f32_32x32x16_bf16 v[64:79], v[208:211], v[120:123], v[64:79]
	ds_read_b128 v[204:207], v226 offset:36864
	s_cbranch_vccz .Lmo_450
	v_and_b32_e32 v153, 64, v172
	v_xor_b32_e32 v152, 32, v172
	v_add_u32_e32 v153, 64, v153
	v_cmp_lt_i32_e32 vcc, v152, v153
	v_max_f32_e32 v153, v229, v229
	v_mov_b32_e32 v155, 0
	v_cndmask_b32_e32 v152, v172, v152, vcc
	v_lshlrev_b32_e32 v152, 2, v152
	ds_bpermute_b32 v152, v152, v229
	v_mov_b32_e32 v229, 0
	s_waitcnt lgkmcnt(0)
	v_max_f32_e32 v152, v152, v152
	v_max_f32_e32 v152, v153, v152
	v_cmp_lt_f32_e32 vcc, s30, v152
	s_and_b64 s[18:19], s[78:79], vcc
	v_cmp_lt_f32_e32 vcc, s29, v152
	s_or_b64 s[78:79], vcc, s[18:19]
	s_and_saveexec_b64 s[18:19], s[78:79]
	v_add_f32_e32 v152, v203, v152
	v_cvt_pk_bf16_f32 v152, v152, 0
	v_lshlrev_b32_e32 v152, 16, v152
	v_sub_f32_e32 v229, v152, v203
	v_mov_b32_e32 v203, v152
	s_or_b64 exec, exec, s[18:19]
	v_exp_f32_e64 v152, -v229
	s_mov_b64 vcc, s[8:9]
	v_sub_f32_e32 v96, v96, v229
	v_sub_f32_e32 v97, v97, v229
	v_pk_mul_f32 v[46:47], v[46:47], v[152:153] op_sel_hi:[1,0]
	v_pk_mul_f32 v[44:45], v[44:45], v[152:153] op_sel_hi:[1,0]
	v_pk_mul_f32 v[42:43], v[42:43], v[152:153] op_sel_hi:[1,0]
	v_pk_mul_f32 v[40:41], v[40:41], v[152:153] op_sel_hi:[1,0]
	v_pk_mul_f32 v[38:39], v[38:39], v[152:153] op_sel_hi:[1,0]
	v_pk_mul_f32 v[36:37], v[36:37], v[152:153] op_sel_hi:[1,0]
	v_pk_mul_f32 v[34:35], v[34:35], v[152:153] op_sel_hi:[1,0]
	v_pk_mul_f32 v[32:33], v[32:33], v[152:153] op_sel_hi:[1,0]
	v_pk_mul_f32 v[30:31], v[30:31], v[152:153] op_sel_hi:[1,0]
	v_pk_mul_f32 v[28:29], v[28:29], v[152:153] op_sel_hi:[1,0]
	v_pk_mul_f32 v[26:27], v[26:27], v[152:153] op_sel_hi:[1,0]
	v_pk_mul_f32 v[24:25], v[24:25], v[152:153] op_sel_hi:[1,0]
	v_pk_mul_f32 v[22:23], v[22:23], v[152:153] op_sel_hi:[1,0]
	v_pk_mul_f32 v[20:21], v[20:21], v[152:153] op_sel_hi:[1,0]
	v_pk_mul_f32 v[18:19], v[18:19], v[152:153] op_sel_hi:[1,0]
	v_pk_mul_f32 v[16:17], v[16:17], v[152:153] op_sel_hi:[1,0]
	v_pk_mul_f32 v[14:15], v[14:15], v[152:153] op_sel_hi:[1,0]
	v_pk_mul_f32 v[12:13], v[12:13], v[152:153] op_sel_hi:[1,0]
	v_pk_mul_f32 v[10:11], v[10:11], v[152:153] op_sel_hi:[1,0]
	v_pk_mul_f32 v[8:9], v[8:9], v[152:153] op_sel_hi:[1,0]
	v_pk_mul_f32 v[6:7], v[6:7], v[152:153] op_sel_hi:[1,0]
	v_pk_mul_f32 v[4:5], v[4:5], v[152:153] op_sel_hi:[1,0]
	v_pk_mul_f32 v[2:3], v[2:3], v[152:153] op_sel_hi:[1,0]
	v_pk_mul_f32 v[0:1], v[0:1], v[152:153] op_sel_hi:[1,0]
	v_xor_b32_e32 v152, 0x80000000, v203
	v_sub_f32_e32 v98, v98, v229
	v_sub_f32_e32 v99, v99, v229
	v_sub_f32_e32 v100, v100, v229
	v_sub_f32_e32 v101, v101, v229
	v_sub_f32_e32 v102, v102, v229
	v_sub_f32_e32 v103, v103, v229
	v_sub_f32_e32 v104, v104, v229
	v_sub_f32_e32 v105, v105, v229
	v_sub_f32_e32 v106, v106, v229
	v_sub_f32_e32 v107, v107, v229
	v_sub_f32_e32 v108, v108, v229
	v_sub_f32_e32 v109, v109, v229
	v_sub_f32_e32 v110, v110, v229
	v_sub_f32_e32 v111, v111, v229
	v_sub_f32_e32 v80, v80, v229
	v_sub_f32_e32 v81, v81, v229
	v_sub_f32_e32 v82, v82, v229
	v_sub_f32_e32 v83, v83, v229
	v_sub_f32_e32 v84, v84, v229
	v_sub_f32_e32 v85, v85, v229
	v_sub_f32_e32 v86, v86, v229
	v_sub_f32_e32 v87, v87, v229
	v_sub_f32_e32 v88, v88, v229
	v_sub_f32_e32 v89, v89, v229
	v_sub_f32_e32 v90, v90, v229
	v_sub_f32_e32 v91, v91, v229
	v_sub_f32_e32 v92, v92, v229
	v_sub_f32_e32 v93, v93, v229
	v_sub_f32_e32 v94, v94, v229
	v_sub_f32_e32 v95, v95, v229
	v_cndmask_b32_sdwa v152, v113, v152, vcc dst_sel:DWORD dst_unused:UNUSED_PAD src0_sel:DWORD src1_sel:WORD_1
	v_mov_b32_e32 v154, 0
	v_mov_b32_e32 v153, 0
	s_branch .Lmo_451

.Lmo_451:
	v_exp_f32_e32 v96, v96
	v_exp_f32_e32 v97, v97
	v_exp_f32_e32 v98, v98
	s_waitcnt lgkmcnt(10)
	v_mfma_f32_32x32x16_bf16 v[48:63], v[212:215], v[120:123], v[48:63]
	ds_read_b128 v[208:211], v228 offset:32768
	v_exp_f32_e32 v99, v99
	v_exp_f32_e32 v100, v100
	v_exp_f32_e32 v101, v101
	s_waitcnt lgkmcnt(10)
	v_mfma_f32_32x32x16_bf16 v[64:79], v[216:219], v[124:127], v[64:79]
	ds_read_b128 v[212:215], v228 offset:36864
	v_exp_f32_e32 v102, v102
	v_exp_f32_e32 v103, v103
	v_cvt_pk_bf16_f32 v224, v96, v97
	v_cvt_pk_bf16_f32 v225, v98, v99
	s_waitcnt lgkmcnt(10)
	v_mfma_f32_32x32x16_bf16 v[48:63], v[220:223], v[124:127], v[48:63]
	ds_read_b128 v[216:219], v254 offset:32768
	v_cvt_pk_bf16_f32 v226, v100, v101
	v_cvt_pk_bf16_f32 v227, v102, v103
	v_exp_f32_e32 v104, v104
	v_exp_f32_e32 v105, v105
	s_waitcnt lgkmcnt(4)
	v_mfma_f32_32x32x16_bf16 v[32:47], v[174:177], v[224:227], v[32:47]
	ds_read_b128 v[220:223], v254 offset:36864
	v_exp_f32_e32 v106, v106
	v_exp_f32_e32 v107, v107
	v_exp_f32_e32 v108, v108
	s_waitcnt lgkmcnt(4)
	v_mfma_f32_32x32x16_bf16 v[16:31], v[204:207], v[224:227], v[16:31]
	v_exp_f32_e32 v109, v109
	v_exp_f32_e32 v110, v110
	v_exp_f32_e32 v111, v111
	v_mfma_f32_32x32x16_bf16 v[64:79], v[230:233], v[128:131], v[64:79]
	v_cvt_pk_bf16_f32 v224, v104, v105
	v_cvt_pk_bf16_f32 v225, v106, v107
	v_cvt_pk_bf16_f32 v226, v108, v109
	v_cvt_pk_bf16_f32 v227, v110, v111
	v_exp_f32_e32 v80, v80
	v_mfma_f32_32x32x16_bf16 v[48:63], v[234:237], v[128:131], v[48:63]
	ds_read_b128 v[230:233], v173 offset:32768
	v_exp_f32_e32 v81, v81
	v_exp_f32_e32 v82, v82
	v_exp_f32_e32 v83, v83
	s_waitcnt lgkmcnt(4)
	v_mfma_f32_32x32x16_bf16 v[32:47], v[208:211], v[224:227], v[32:47]
	ds_read_b128 v[234:237], v173 offset:36864
	v_exp_f32_e32 v84, v84
	v_exp_f32_e32 v85, v85
	v_exp_f32_e32 v86, v86
	s_waitcnt lgkmcnt(4)
	v_mfma_f32_32x32x16_bf16 v[16:31], v[212:215], v[224:227], v[16:31]
	v_exp_f32_e32 v87, v87
	v_cvt_pk_bf16_f32 v224, v80, v81
	v_cvt_pk_bf16_f32 v225, v82, v83
	v_cvt_pk_bf16_f32 v226, v84, v85
	v_cvt_pk_bf16_f32 v227, v86, v87
	v_mfma_f32_32x32x16_bf16 v[64:79], v[238:241], v[132:135], v[64:79]
	v_exp_f32_e32 v88, v88
	v_exp_f32_e32 v89, v89
	v_exp_f32_e32 v90, v90
	v_mfma_f32_32x32x16_bf16 v[48:63], v[242:245], v[132:135], v[48:63]
	v_exp_f32_e32 v91, v91
	v_exp_f32_e32 v92, v92
	v_exp_f32_e32 v93, v93
	s_waitcnt lgkmcnt(3)
	v_mfma_f32_32x32x16_bf16 v[32:47], v[216:219], v[224:227], v[32:47]
	v_exp_f32_e32 v94, v94
	v_exp_f32_e32 v95, v95
	v_pk_add_f32 v[96:97], v[80:81], v[96:97]
	s_waitcnt lgkmcnt(2)
	v_mfma_f32_32x32x16_bf16 v[16:31], v[220:223], v[224:227], v[16:31]
	v_cvt_pk_bf16_f32 v224, v88, v89
	v_cvt_pk_bf16_f32 v225, v90, v91
	v_cvt_pk_bf16_f32 v226, v92, v93
	v_cvt_pk_bf16_f32 v227, v94, v95
	v_pk_add_f32 v[98:99], v[82:83], v[98:99]
	v_mfma_f32_32x32x16_bf16 v[64:79], v[246:249], v[136:139], v[64:79]
	v_pk_add_f32 v[100:101], v[84:85], v[100:101]
	v_pk_add_f32 v[102:103], v[86:87], v[102:103]
	v_pk_add_f32 v[104:105], v[88:89], v[104:105]
	v_mfma_f32_32x32x16_bf16 v[48:63], v[250:253], v[136:139], v[48:63]
	v_pk_add_f32 v[106:107], v[90:91], v[106:107]
	v_pk_add_f32 v[108:109], v[92:93], v[108:109]
	v_pk_add_f32 v[110:111], v[94:95], v[110:111]
	s_waitcnt lgkmcnt(1)
	v_mfma_f32_32x32x16_bf16 v[32:47], v[230:233], v[224:227], v[32:47]
	v_pk_add_f32 v[0:1], v[96:97], v[0:1]
	v_pk_add_f32 v[2:3], v[98:99], v[2:3]
	v_pk_add_f32 v[4:5], v[100:101], v[4:5]
	s_waitcnt lgkmcnt(0)
	v_mfma_f32_32x32x16_bf16 v[16:31], v[234:237], v[224:227], v[16:31]
	v_cmp_neq_f32_e32 vcc, 0, v229
	v_pk_add_f32 v[6:7], v[102:103], v[6:7]
	v_pk_add_f32 v[8:9], v[104:105], v[8:9]
	v_pk_add_f32 v[10:11], v[106:107], v[10:11]
	v_pk_add_f32 v[12:13], v[108:109], v[12:13]
	v_pk_add_f32 v[14:15], v[110:111], v[14:15]
	s_cbranch_vccz .Lmo_453
	v_sub_f32_e32 v79, v79, v229
	v_sub_f32_e32 v78, v78, v229
	v_sub_f32_e32 v77, v77, v229
	v_sub_f32_e32 v76, v76, v229
	v_sub_f32_e32 v75, v75, v229
	v_sub_f32_e32 v74, v74, v229
	v_sub_f32_e32 v73, v73, v229
	v_sub_f32_e32 v72, v72, v229
	v_sub_f32_e32 v71, v71, v229
	v_sub_f32_e32 v70, v70, v229
	v_sub_f32_e32 v69, v69, v229
	v_sub_f32_e32 v68, v68, v229
	v_sub_f32_e32 v67, v67, v229
	v_sub_f32_e32 v66, v66, v229
	v_sub_f32_e32 v65, v65, v229
	v_sub_f32_e32 v64, v64, v229
	v_sub_f32_e32 v63, v63, v229
	v_sub_f32_e32 v62, v62, v229
	v_sub_f32_e32 v61, v61, v229
	v_sub_f32_e32 v60, v60, v229
	v_sub_f32_e32 v59, v59, v229
	v_sub_f32_e32 v58, v58, v229
	v_sub_f32_e32 v57, v57, v229
	v_sub_f32_e32 v56, v56, v229
	v_sub_f32_e32 v55, v55, v229
	v_sub_f32_e32 v54, v54, v229
	v_sub_f32_e32 v53, v53, v229
	v_sub_f32_e32 v52, v52, v229
	v_sub_f32_e32 v51, v51, v229
	v_sub_f32_e32 v50, v50, v229
	v_sub_f32_e32 v49, v49, v229
	v_sub_f32_e32 v48, v48, v229

.Lmo_455:
	s_or_b64 exec, exec, s[78:79]
.Lmo_456:
	s_or_b64 exec, exec, s[86:87]
	s_add_i32 s69, s73, 2
	s_cmp_lt_u32 s69, s70
	s_cselect_b64 s[18:19], -1, 0
	s_cmp_ge_u32 s69, s70
	s_cbranch_scc0 .Lmo_463
	s_cmp_ge_u32 s74, s70
	s_cbranch_scc0 .Lmo_466
